# final row pass: gain vectors hoisted into registers, serialising waits removed
# speedup vs baseline: 1.0001x; 1.0001x over previous
; template <int MODE>
; __device__ __forceinline__ void row_pass(const Params& p, int wave, int lane, const float* gpost, const float* gnext, const bf16_t* Dsrc, bf16_t* U, float coef, int rbeg) {
;     const int gw = blockIdx.x * 8 + wave, NGW = gridDim.x * 8;
;     for (int r = rbeg + gw; r < ROWSP; r += 2 * NGW) {
;         f32x4 ha[8], hb[8]; u32x2 da[8], db[8];
;         row_load<MODE>(p, r, lane, Dsrc, ha, da);
;         row_load<MODE>(p, r + NGW, lane, Dsrc, hb, db);
;         row_finish<MODE>(p, r, lane, gpost, gnext, U, coef, ha, da);
;         row_finish<MODE>(p, r + NGW, lane, gpost, gnext, U, coef, hb, db);
;     }
; }
; __global__ void __launch_bounds__(512, 2) fwd_kernel(Params p) {
;     ...
;                 row_pass<3>(p, wave, lane, p.in[24], nullptr, Breg, nullptr, 0.5f, 16384);
.LBB0_1897:
	s_lshl_b32 s0, s2, 3
	s_add_i32 s0, s0, s10
	s_add_i32 s2, s0, 0x4000
	s_cmp_gt_i32 s2, 0x80ff
	s_cbranch_scc1 .LBB0_1908
	global_load_dwordx4 v[176:179], v[74:75], off
	global_load_dwordx4 v[180:183], v[74:75], off offset:1024
	global_load_dwordx4 v[184:187], v[74:75], off offset:2048
	global_load_dwordx4 v[188:191], v[74:75], off offset:3072
	global_load_dwordx4 v[192:195], v[76:77], off
	global_load_dwordx4 v[196:199], v[78:79], off
	global_load_dwordx4 v[200:203], v[80:81], off
	global_load_dwordx4 v[204:207], v[82:83], off
	s_waitcnt vmcnt(0)
	v_lshlrev_b32_e32 v0, 3, v64
	v_mov_b32_e32 v1, 0
	v_lshl_add_u64 v[2:3], s[16:17], 0, v[0:1]
	s_mov_b64 s[0:1], 0xa2f1d00
	s_lshl_b32 s8, s22, 3
	v_lshl_add_u64 v[84:85], v[2:3], 0, s[0:1]
	v_mov_b32_e32 v120, 0x358637bd
	s_mov_b32 s9, 0x800000
	v_mov_b32_e32 v0, v1
	v_mov_b32_e32 v2, v1
	v_mov_b32_e32 v3, v1
	v_mov_b32_e32 v32, v1
	v_mov_b32_e32 v33, v1
	v_mov_b32_e32 v34, v1
	v_mov_b32_e32 v35, v1
	v_mov_b32_e32 v40, v1
	v_mov_b32_e32 v41, v1
	v_mov_b32_e32 v42, v1
	v_mov_b32_e32 v43, v1
	v_mov_b32_e32 v44, v1
	v_mov_b32_e32 v45, v1
	v_mov_b32_e32 v46, v1
	v_mov_b32_e32 v47, v1
	v_mov_b32_e32 v48, v1
	v_mov_b32_e32 v49, v1
	v_mov_b32_e32 v50, v1
	v_mov_b32_e32 v51, v1
	v_mov_b32_e32 v52, v1
	v_mov_b32_e32 v53, v1
	v_mov_b32_e32 v54, v1
	v_mov_b32_e32 v55, v1
	v_mov_b32_e32 v56, v1
	v_mov_b32_e32 v57, v1
	v_mov_b32_e32 v58, v1
	v_mov_b32_e32 v59, v1
	v_mov_b32_e32 v60, v1
	v_mov_b32_e32 v61, v1
	v_mov_b32_e32 v62, v1
	v_mov_b32_e32 v63, v1
	s_branch .LBB0_1900

; template <int MODE>
; __device__ __forceinline__ void row_load(const Params& p, int r, int lane, const bf16_t* Dsrc, f32x4 (&h)[8], u32x2 (&dw)[8]) {
;     if (r >= ROWS || (MODE >= 2 && r >= NTOKR)) return;
;     const f32x4* hs = (const f32x4*)((MODE <= 1) ? h0row(p, r) : (const float*)hrow(p, r));
; #pragma unroll
;     for (int j = 0; j < 8; ++j) h[j] = __builtin_nontemporal_load(&hs[lane + 64 * j]);
;     if (MODE >= 1) { const u32x2* dp = (const u32x2*)(Dsrc + (size_t)r * DM);
; #pragma unroll
;         for (int j = 0; j < 8; ++j) dw[j] = __builtin_nontemporal_load(&dp[lane + 64 * j]); }
.LBB0_1900:
	s_cmp_lt_i32 s2, 0x8000
	s_cselect_b64 s[6:7], -1, 0
	s_cmpk_gt_i32 s2, 0x7fff
	v_lshlrev_b32_e32 v125, 4, v64
	v_lshlrev_b32_e32 v124, 4, v66
	v_lshlrev_b32_e32 v123, 4, v68
	v_lshlrev_b32_e32 v122, 4, v70
	v_lshlrev_b32_e32 v121, 4, v72
	s_cbranch_scc1 .LBB0_1902
	s_ashr_i32 s3, s2, 31
	s_lshl_b64 s[0:1], s[2:3], 13
	s_add_u32 s0, s14, s0
	s_addc_u32 s1, s15, s1
	global_load_dwordx4 v[0:3], v125, s[0:1] nt
	global_load_dwordx4 v[32:35], v125, s[0:1] offset:1024 nt
	global_load_dwordx4 v[40:43], v125, s[0:1] offset:2048 nt
	global_load_dwordx4 v[44:47], v125, s[0:1] offset:3072 nt
	global_load_dwordx4 v[48:51], v124, s[0:1] nt
	global_load_dwordx4 v[52:55], v123, s[0:1] nt
	global_load_dwordx4 v[56:59], v122, s[0:1] nt
	global_load_dwordx4 v[60:63], v121, s[0:1] nt
	s_lshl_b64 s[0:1], s[2:3], 12
	v_lshl_add_u64 v[116:117], v[84:85], 0, s[0:1]
	flat_load_dwordx2 v[102:103], v[116:117] nt
	flat_load_dwordx2 v[104:105], v[116:117] offset:512 nt
	flat_load_dwordx2 v[106:107], v[116:117] offset:1024 nt
	flat_load_dwordx2 v[108:109], v[116:117] offset:1536 nt
	flat_load_dwordx2 v[110:111], v[116:117] offset:2048 nt
	flat_load_dwordx2 v[112:113], v[116:117] offset:2560 nt
	flat_load_dwordx2 v[114:115], v[116:117] offset:3072 nt
	s_nop 0
	flat_load_dwordx2 v[116:117], v[116:117] offset:3584 nt

; template <int MODE>
; __device__ __forceinline__ void row_load(const Params& p, int r, int lane, const bf16_t* Dsrc, f32x4 (&h)[8], u32x2 (&dw)[8]) {
;     if (r >= ROWS || (MODE >= 2 && r >= NTOKR)) return;
;     const f32x4* hs = (const f32x4*)((MODE <= 1) ? h0row(p, r) : (const float*)hrow(p, r));
; #pragma unroll
;     for (int j = 0; j < 8; ++j) h[j] = __builtin_nontemporal_load(&hs[lane + 64 * j]);
;     if (MODE >= 1) { const u32x2* dp = (const u32x2*)(Dsrc + (size_t)r * DM);
; #pragma unroll
;         for (int j = 0; j < 8; ++j) dw[j] = __builtin_nontemporal_load(&dp[lane + 64 * j]); }
; template <int MODE>
; __device__ __forceinline__ void row_finish(const Params& p, int r, int lane, const float* gpost, const float* gnext, bf16_t* U, float coef, f32x4 (&h)[8], const u32x2 (&dw)[8]) {
;     ...
;     if (MODE >= 1) {
;         f32x4 d[8]; float ss = 0.f;
; #pragma unroll
;         for (int j = 0; j < 8; ++j) { const u32x2 w = dw[j]; d[j] = (f32x4){bflo(w.x), bfhi(w.x), bflo(w.y), bfhi(w.y)};
;             ss += (d[j].x * d[j].x + d[j].y * d[j].y) + (d[j].z * d[j].z + d[j].w * d[j].w); }
;         ss = wave_sum(ss);
;         const float rs = rsqrtf(ss * (1.f / DM) + EPS) * coef;
.Lrp3_bwait:
	s_waitcnt vmcnt(0) lgkmcnt(0)
	s_branch .LBB0_1907
.LBB0_1905:
	s_ashr_i32 s1, s0, 31
	s_lshl_b64 s[10:11], s[0:1], 13
	s_add_u32 s10, s14, s10
	s_addc_u32 s11, s15, s11
	global_load_dwordx4 v[4:7], v125, s[10:11] nt
	global_load_dwordx4 v[8:11], v125, s[10:11] offset:1024 nt
	global_load_dwordx4 v[12:15], v125, s[10:11] offset:2048 nt
	global_load_dwordx4 v[16:19], v125, s[10:11] offset:3072 nt
	global_load_dwordx4 v[20:23], v124, s[10:11] nt
	global_load_dwordx4 v[24:27], v123, s[10:11] nt
	global_load_dwordx4 v[28:31], v122, s[10:11] nt
	global_load_dwordx4 v[36:39], v121, s[10:11] nt
	s_lshl_b64 s[10:11], s[0:1], 12
	v_lshl_add_u64 v[100:101], v[84:85], 0, s[10:11]
	flat_load_dwordx2 v[86:87], v[100:101] nt
	flat_load_dwordx2 v[88:89], v[100:101] offset:512 nt
	flat_load_dwordx2 v[90:91], v[100:101] offset:1024 nt
	flat_load_dwordx2 v[92:93], v[100:101] offset:1536 nt
	flat_load_dwordx2 v[94:95], v[100:101] offset:2048 nt
	flat_load_dwordx2 v[96:97], v[100:101] offset:2560 nt
	flat_load_dwordx2 v[98:99], v[100:101] offset:3072 nt
	s_nop 0
	flat_load_dwordx2 v[100:101], v[100:101] offset:3584 nt
	s_andn2_b64 vcc, exec, s[6:7]
	s_cbranch_vccnz .LBB0_1904
.LBB0_1906:
	s_waitcnt vmcnt(0) lgkmcnt(0)
	v_and_b32_e32 v133, 0xffff0000, v102
	v_and_b32_e32 v132, 0xffff0000, v104
	v_and_b32_e32 v137, 0xffff0000, v103
	v_and_b32_e32 v136, 0xffff0000, v105
	v_lshlrev_b32_e32 v131, 16, v102
	v_lshlrev_b32_e32 v130, 16, v104
	v_lshlrev_b32_e32 v135, 16, v103
	v_lshlrev_b32_e32 v134, 16, v105
	v_pk_mul_f32 v[118:119], v[132:133], v[132:133]
	v_pk_mul_f32 v[126:127], v[136:137], v[136:137]
	v_pk_fma_f32 v[118:119], v[130:131], v[130:131], v[118:119]
	v_pk_fma_f32 v[126:127], v[134:135], v[134:135], v[126:127]
	v_and_b32_e32 v141, 0xffff0000, v107
	v_pk_add_f32 v[118:119], v[118:119], v[126:127]
	v_and_b32_e32 v140, 0xffff0000, v106
	v_pk_add_f32 v[126:127], v[118:119], v[118:119] op_sel_hi:[0,1]
	v_lshlrev_b32_e32 v139, 16, v107
	v_lshlrev_b32_e32 v138, 16, v106
	v_pk_mul_f32 v[118:119], v[140:141], v[140:141]
	v_lshlrev_b32_e32 v142, 16, v108
	v_pk_fma_f32 v[118:119], v[138:139], v[138:139], v[118:119]
	v_lshlrev_b32_e32 v146, 16, v109
	v_pk_add_f32 v[128:129], v[118:119], v[118:119] op_sel_hi:[0,1]
	v_mul_f32_e32 v119, v142, v142
	v_and_b32_e32 v147, 0xffff0000, v109
	v_mul_f32_e32 v118, v146, v146
	v_and_b32_e32 v143, 0xffff0000, v108
	v_pk_fma_f32 v[148:149], v[146:147], v[146:147], v[118:119] op_sel_hi:[1,1,0]
	v_lshlrev_b32_e32 v118, 16, v110
	v_mul_f32_e32 v145, v143, v143
	v_mov_b32_e32 v144, v118
	v_and_b32_e32 v159, 0xffff0000, v110
	v_lshlrev_b32_e32 v150, 16, v111
	v_and_b32_e32 v151, 0xffff0000, v111
	v_pk_add_f32 v[144:145], v[118:119], v[144:145]
	v_mul_f32_e32 v148, v159, v159
	v_mul_f32_e32 v128, v150, v150
	v_mul_f32_e32 v126, v151, v151
	v_mul_f32_e32 v152, v118, v118
	v_mov_b32_e32 v153, v145
	v_pk_add_f32 v[144:145], v[152:153], v[148:149]
	v_pk_add_f32 v[126:127], v[128:129], v[126:127]
	v_and_b32_e32 v153, 0xffff0000, v113
	v_pk_add_f32 v[126:127], v[144:145], v[126:127]
	v_and_b32_e32 v152, 0xffff0000, v112
	v_pk_add_f32 v[144:145], v[126:127], v[126:127] op_sel_hi:[0,1]
	v_mov_b64_e32 v[126:127], v[176:177]
	v_mov_b64_e32 v[128:129], v[178:179]
	v_lshlrev_b32_e32 v149, 16, v113
	v_lshlrev_b32_e32 v148, 16, v112
	v_pk_mul_f32 v[154:155], v[152:153], v[152:153]
	v_lshlrev_b32_e32 v156, 16, v114
	v_and_b32_e32 v157, 0xffff0000, v114
	v_lshlrev_b32_e32 v164, 16, v115
	v_lshlrev_b32_e32 v160, 16, v116
	v_pk_fma_f32 v[154:155], v[148:149], v[148:149], v[154:155]
	v_mul_f32_e32 v161, v156, v156
	v_mul_f32_e32 v163, v157, v157
	v_and_b32_e32 v165, 0xffff0000, v115
	v_mul_f32_e32 v144, v164, v164
	v_mov_b32_e32 v162, v160
	v_pk_add_f32 v[154:155], v[154:155], v[154:155] op_sel_hi:[0,1]
	v_pk_fma_f32 v[166:167], v[164:165], v[164:165], v[144:145] op_sel_hi:[1,1,0]
	v_and_b32_e32 v172, 0xffff0000, v116
	v_lshlrev_b32_e32 v168, 16, v117
	v_and_b32_e32 v169, 0xffff0000, v117
	v_pk_add_f32 v[162:163], v[160:161], v[162:163]
	v_mul_f32_e32 v166, v172, v172
	v_mul_f32_e32 v154, v168, v168
	v_mul_f32_e32 v144, v169, v169
	v_mul_f32_e32 v170, v160, v160
	v_mov_b32_e32 v171, v163
	v_pk_add_f32 v[162:163], v[170:171], v[166:167]
	v_pk_add_f32 v[144:145], v[154:155], v[144:145]
	s_ashr_i32 s3, s2, 31
	v_pk_add_f32 v[144:145], v[162:163], v[144:145]
	v_mov_b32_e32 v154, v131
	v_add_f32_e32 v119, v144, v145
	ds_bpermute_b32 v144, v65, v119
	v_mov_b32_e32 v155, v133
	s_lshl_b64 s[2:3], s[2:3], 13
	s_add_u32 s2, s14, s2
	s_addc_u32 s3, s15, s3
	s_waitcnt lgkmcnt(0)
	v_add_f32_e32 v119, v119, v144
	ds_bpermute_b32 v144, v67, v119
	v_mov_b32_e32 v131, v132
	v_mov_b32_e32 v161, v172
	s_waitcnt lgkmcnt(0)
	v_add_f32_e32 v119, v119, v144
	ds_bpermute_b32 v144, v69, v119
	s_waitcnt lgkmcnt(0)
	v_add_f32_e32 v119, v119, v144
	ds_bpermute_b32 v144, v71, v119
	s_waitcnt lgkmcnt(0)
	v_add_f32_e32 v119, v119, v144
	ds_bpermute_b32 v144, v73, v119
	s_waitcnt lgkmcnt(0)
	v_add_f32_e32 v119, v119, v144
	ds_bpermute_b32 v144, v158, v119
	s_waitcnt lgkmcnt(0)
; template <int MODE>
; __device__ __forceinline__ void row_finish(const Params& p, int r, int lane, const float* gpost, const float* gnext, bf16_t* U, float coef, f32x4 (&h)[8], const u32x2 (&dw)[8]) {
;     ...
;         ss = wave_sum(ss);
;         const float rs = rsqrtf(ss * (1.f / DM) + EPS) * coef;
;         f32x4* hd = (f32x4*)hrow(p, r);
; #pragma unroll
;         for (int j = 0; j < 8; ++j) { const f32x4 g = ((const f32x4*)gpost)[lane + 64 * j]; h[j] = h[j] + d[j] * g * rs; __builtin_nontemporal_store(h[j], &hd[lane + 64 * j]); }
	v_add_f32_e32 v119, v119, v144
	v_fmamk_f32 v119, v119, 0x3a000000, v120
	v_mul_f32_e32 v144, 0x4b800000, v119
	v_cmp_gt_f32_e32 vcc, s9, v119
	v_pk_mul_f32 v[126:127], v[154:155], v[126:127]
	v_cndmask_b32_e32 v119, v119, v144, vcc
	v_rsq_f32_e32 v119, v119
	v_mov_b32_e32 v154, v135
	v_mov_b32_e32 v155, v137
	v_pk_mul_f32 v[128:129], v[154:155], v[128:129]
	v_mul_f32_e32 v144, 0x45800000, v119
	v_cndmask_b32_e32 v119, v119, v144, vcc
	v_mul_f32_e32 v144, 0.5, v119
	v_pk_fma_f32 v[2:3], v[128:129], v[144:145], v[2:3] op_sel_hi:[1,0,1]
	v_pk_fma_f32 v[0:1], v[126:127], v[144:145], v[0:1] op_sel_hi:[1,0,1]
	global_store_dwordx4 v125, v[0:3], s[2:3] nt
	v_mov_b64_e32 v[126:127], v[180:181]
	v_mov_b64_e32 v[128:129], v[182:183]
	v_mov_b32_e32 v135, v136
	v_mov_b32_e32 v119, v159
	v_pk_mul_f32 v[126:127], v[130:131], v[126:127]
	v_pk_mul_f32 v[128:129], v[134:135], v[128:129]
	v_pk_fma_f32 v[32:33], v[126:127], v[144:145], v[32:33] op_sel_hi:[1,0,1]
	v_pk_fma_f32 v[34:35], v[128:129], v[144:145], v[34:35] op_sel_hi:[1,0,1]
	global_store_dwordx4 v125, v[32:35], s[2:3] offset:1024 nt
	v_mov_b64_e32 v[126:127], v[184:185]
	v_mov_b64_e32 v[128:129], v[186:187]
	v_mov_b32_e32 v130, v138
	v_mov_b32_e32 v131, v140
	v_mov_b32_e32 v140, v139
	v_pk_mul_f32 v[126:127], v[126:127], v[130:131]
	v_pk_mul_f32 v[128:129], v[128:129], v[140:141]
	v_pk_fma_f32 v[40:41], v[126:127], v[144:145], v[40:41] op_sel_hi:[1,0,1]
	v_pk_fma_f32 v[42:43], v[128:129], v[144:145], v[42:43] op_sel_hi:[1,0,1]
	global_store_dwordx4 v125, v[40:43], s[2:3] offset:2048 nt
	v_mov_b64_e32 v[126:127], v[188:189]
	v_mov_b64_e32 v[128:129], v[190:191]
	v_pk_mul_f32 v[126:127], v[142:143], v[126:127]
	v_pk_mul_f32 v[128:129], v[146:147], v[128:129]
	v_pk_fma_f32 v[44:45], v[126:127], v[144:145], v[44:45] op_sel_hi:[1,0,1]
	v_pk_fma_f32 v[46:47], v[128:129], v[144:145], v[46:47] op_sel_hi:[1,0,1]
	global_store_dwordx4 v125, v[44:47], s[2:3] offset:3072 nt
	v_mov_b64_e32 v[126:127], v[192:193]
	v_mov_b64_e32 v[128:129], v[194:195]
	v_pk_mul_f32 v[118:119], v[118:119], v[126:127]
	v_pk_mul_f32 v[126:127], v[150:151], v[128:129]
	v_pk_fma_f32 v[48:49], v[118:119], v[144:145], v[48:49] op_sel_hi:[1,0,1]
	v_pk_fma_f32 v[50:51], v[126:127], v[144:145], v[50:51] op_sel_hi:[1,0,1]
	global_store_dwordx4 v124, v[48:51], s[2:3] nt
	v_mov_b64_e32 v[126:127], v[196:197]
	v_mov_b64_e32 v[128:129], v[198:199]
	v_mov_b32_e32 v118, v148
	v_mov_b32_e32 v119, v152
	v_mov_b32_e32 v152, v149
	v_pk_mul_f32 v[118:119], v[126:127], v[118:119]
	v_pk_mul_f32 v[126:127], v[128:129], v[152:153]
	v_pk_fma_f32 v[52:53], v[144:145], v[118:119], v[52:53] op_sel_hi:[0,1,1]
	v_pk_fma_f32 v[54:55], v[144:145], v[126:127], v[54:55] op_sel_hi:[0,1,1]
	global_store_dwordx4 v123, v[52:55], s[2:3] nt
	v_mov_b64_e32 v[126:127], v[200:201]
	v_mov_b64_e32 v[128:129], v[202:203]
	v_pk_mul_f32 v[118:119], v[156:157], v[126:127]
	v_pk_mul_f32 v[126:127], v[164:165], v[128:129]
	v_pk_fma_f32 v[56:57], v[144:145], v[118:119], v[56:57] op_sel_hi:[0,1,1]
	v_pk_fma_f32 v[58:59], v[144:145], v[126:127], v[58:59] op_sel_hi:[0,1,1]
	global_store_dwordx4 v122, v[56:59], s[2:3] nt
	v_mov_b64_e32 v[126:127], v[204:205]
	v_mov_b64_e32 v[128:129], v[206:207]
	v_pk_mul_f32 v[118:119], v[160:161], v[126:127]
	v_pk_mul_f32 v[126:127], v[168:169], v[128:129]
	v_pk_fma_f32 v[60:61], v[144:145], v[118:119], v[60:61] op_sel_hi:[0,1,1]
	v_pk_fma_f32 v[62:63], v[144:145], v[126:127], v[62:63] op_sel_hi:[0,1,1]
	global_store_dwordx4 v121, v[60:63], s[2:3] nt
	s_andn2_b64 vcc, exec, s[4:5]
	s_cbranch_vccnz .LBB0_1899
.LBB0_1907:
	v_and_b32_e32 v131, 0xffff0000, v86
	v_and_b32_e32 v130, 0xffff0000, v88
	v_and_b32_e32 v135, 0xffff0000, v87
	v_and_b32_e32 v134, 0xffff0000, v89
	v_lshlrev_b32_e32 v119, 16, v86
	v_lshlrev_b32_e32 v118, 16, v88
	v_lshlrev_b32_e32 v133, 16, v87
	v_lshlrev_b32_e32 v132, 16, v89
	v_pk_mul_f32 v[126:127], v[130:131], v[130:131]
	v_pk_mul_f32 v[128:129], v[134:135], v[134:135]
	v_pk_fma_f32 v[126:127], v[118:119], v[118:119], v[126:127]
	v_pk_fma_f32 v[128:129], v[132:133], v[132:133], v[128:129]
	v_and_b32_e32 v139, 0xffff0000, v91
	v_pk_add_f32 v[126:127], v[126:127], v[128:129]
	v_and_b32_e32 v138, 0xffff0000, v90
	v_pk_add_f32 v[126:127], v[126:127], v[126:127] op_sel_hi:[0,1]
	v_lshlrev_b32_e32 v137, 16, v91
	v_lshlrev_b32_e32 v136, 16, v90
	v_pk_mul_f32 v[128:129], v[138:139], v[138:139]
	v_lshlrev_b32_e32 v140, 16, v92
	v_and_b32_e32 v141, 0xffff0000, v92
	v_lshlrev_b32_e32 v146, 16, v93
	v_lshlrev_b32_e32 v142, 16, v94
	v_pk_fma_f32 v[128:129], v[136:137], v[136:137], v[128:129]
	v_mul_f32_e32 v143, v140, v140
	v_mul_f32_e32 v145, v141, v141
	v_and_b32_e32 v147, 0xffff0000, v93
	v_mul_f32_e32 v126, v146, v146
	v_mov_b32_e32 v144, v142
	v_pk_add_f32 v[128:129], v[128:129], v[128:129] op_sel_hi:[0,1]
	v_pk_fma_f32 v[148:149], v[146:147], v[146:147], v[126:127] op_sel_hi:[1,1,0]
	v_and_b32_e32 v159, 0xffff0000, v94
	v_lshlrev_b32_e32 v150, 16, v95
	v_and_b32_e32 v151, 0xffff0000, v95
	v_pk_add_f32 v[144:145], v[142:143], v[144:145]
	v_mul_f32_e32 v148, v159, v159
	v_mul_f32_e32 v128, v150, v150
	v_mul_f32_e32 v126, v151, v151
	v_mul_f32_e32 v152, v142, v142
	v_mov_b32_e32 v153, v145
	v_pk_add_f32 v[144:145], v[152:153], v[148:149]
	v_pk_add_f32 v[126:127], v[128:129], v[126:127]
	v_and_b32_e32 v153, 0xffff0000, v97
	v_pk_add_f32 v[126:127], v[144:145], v[126:127]
	v_and_b32_e32 v152, 0xffff0000, v96
	v_pk_add_f32 v[144:145], v[126:127], v[126:127] op_sel_hi:[0,1]
	v_mov_b64_e32 v[126:127], v[176:177]
	v_mov_b64_e32 v[128:129], v[178:179]
	v_lshlrev_b32_e32 v149, 16, v97
	v_lshlrev_b32_e32 v148, 16, v96
	v_pk_mul_f32 v[154:155], v[152:153], v[152:153]
	v_lshlrev_b32_e32 v156, 16, v98
	v_and_b32_e32 v157, 0xffff0000, v98
	v_lshlrev_b32_e32 v164, 16, v99
	v_lshlrev_b32_e32 v160, 16, v100
	v_pk_fma_f32 v[154:155], v[148:149], v[148:149], v[154:155]
	v_mul_f32_e32 v161, v156, v156
	v_mul_f32_e32 v163, v157, v157
	v_and_b32_e32 v165, 0xffff0000, v99
	v_mul_f32_e32 v144, v164, v164
	v_mov_b32_e32 v162, v160
	v_pk_add_f32 v[154:155], v[154:155], v[154:155] op_sel_hi:[0,1]
	v_pk_fma_f32 v[166:167], v[164:165], v[164:165], v[144:145] op_sel_hi:[1,1,0]
	v_and_b32_e32 v172, 0xffff0000, v100
	v_lshlrev_b32_e32 v168, 16, v101
	v_and_b32_e32 v169, 0xffff0000, v101
	v_pk_add_f32 v[162:163], v[160:161], v[162:163]
	v_mul_f32_e32 v166, v172, v172
	v_mul_f32_e32 v154, v168, v168
	v_mul_f32_e32 v144, v169, v169
	v_mul_f32_e32 v170, v160, v160
	v_mov_b32_e32 v171, v163
	v_pk_add_f32 v[162:163], v[170:171], v[166:167]
	v_pk_add_f32 v[144:145], v[154:155], v[144:145]
	s_ashr_i32 s1, s0, 31
	v_pk_add_f32 v[144:145], v[162:163], v[144:145]
	v_mov_b32_e32 v154, v119
	v_add_f32_e32 v143, v144, v145
	ds_bpermute_b32 v144, v65, v143
	v_mov_b32_e32 v155, v131
	s_lshl_b64 s[2:3], s[0:1], 13
	s_add_u32 s2, s14, s2
	s_addc_u32 s3, s15, s3
	s_waitcnt lgkmcnt(0)
; template <int MODE>
; __device__ __forceinline__ void row_finish(const Params& p, int r, int lane, const float* gpost, const float* gnext, bf16_t* U, float coef, f32x4 (&h)[8], const u32x2 (&dw)[8]) {
;     ...
;         ss = wave_sum(ss);
;         const float rs = rsqrtf(ss * (1.f / DM) + EPS) * coef;
;         f32x4* hd = (f32x4*)hrow(p, r);
; #pragma unroll
;         for (int j = 0; j < 8; ++j) { const f32x4 g = ((const f32x4*)gpost)[lane + 64 * j]; h[j] = h[j] + d[j] * g * rs; __builtin_nontemporal_store(h[j], &hd[lane + 64 * j]); }
; template <int MODE>
; __device__ __forceinline__ void row_pass(const Params& p, int wave, int lane, const float* gpost, const float* gnext, const bf16_t* Dsrc, bf16_t* U, float coef, int rbeg) {
;     ...
;         row_finish<MODE>(p, r + NGW, lane, gpost, gnext, U, coef, hb, db);
	v_add_f32_e32 v143, v143, v144
	ds_bpermute_b32 v144, v67, v143
	v_mov_b32_e32 v119, v130
	v_mov_b32_e32 v161, v172
	s_waitcnt lgkmcnt(0)
	v_add_f32_e32 v143, v143, v144
	ds_bpermute_b32 v144, v69, v143
	s_waitcnt lgkmcnt(0)
	v_add_f32_e32 v143, v143, v144
	ds_bpermute_b32 v144, v71, v143
	s_waitcnt lgkmcnt(0)
	v_add_f32_e32 v143, v143, v144
	ds_bpermute_b32 v144, v73, v143
	s_waitcnt lgkmcnt(0)
	v_add_f32_e32 v143, v143, v144
	ds_bpermute_b32 v144, v158, v143
	s_waitcnt lgkmcnt(0)
	v_add_f32_e32 v143, v143, v144
	v_fmamk_f32 v143, v143, 0x3a000000, v120
	v_mul_f32_e32 v144, 0x4b800000, v143
	v_cmp_gt_f32_e32 vcc, s9, v143
	v_pk_mul_f32 v[126:127], v[154:155], v[126:127]
	v_cndmask_b32_e32 v143, v143, v144, vcc
	v_rsq_f32_e32 v143, v143
	v_mov_b32_e32 v154, v133
	v_mov_b32_e32 v155, v135
	v_pk_mul_f32 v[128:129], v[154:155], v[128:129]
	v_mul_f32_e32 v144, 0x45800000, v143
	v_cndmask_b32_e32 v143, v143, v144, vcc
	v_mul_f32_e32 v144, 0.5, v143
	v_pk_fma_f32 v[6:7], v[128:129], v[144:145], v[6:7] op_sel_hi:[1,0,1]
	v_pk_fma_f32 v[4:5], v[126:127], v[144:145], v[4:5] op_sel_hi:[1,0,1]
	global_store_dwordx4 v125, v[4:7], s[2:3] nt
	v_mov_b64_e32 v[126:127], v[180:181]
	v_mov_b64_e32 v[128:129], v[182:183]
	v_mov_b32_e32 v133, v134
	v_mov_b32_e32 v143, v159
	v_pk_mul_f32 v[128:129], v[132:133], v[128:129]
	v_pk_mul_f32 v[118:119], v[118:119], v[126:127]
	v_pk_fma_f32 v[10:11], v[128:129], v[144:145], v[10:11] op_sel_hi:[1,0,1]
	v_pk_fma_f32 v[8:9], v[118:119], v[144:145], v[8:9] op_sel_hi:[1,0,1]
	global_store_dwordx4 v125, v[8:11], s[2:3] offset:1024 nt
	v_mov_b64_e32 v[126:127], v[184:185]
	v_mov_b64_e32 v[128:129], v[186:187]
	v_mov_b32_e32 v118, v137
	v_mov_b32_e32 v119, v139
	v_mov_b32_e32 v137, v138
	v_pk_mul_f32 v[118:119], v[128:129], v[118:119]
	v_pk_mul_f32 v[126:127], v[126:127], v[136:137]
	v_pk_fma_f32 v[14:15], v[118:119], v[144:145], v[14:15] op_sel_hi:[1,0,1]
	v_pk_fma_f32 v[12:13], v[126:127], v[144:145], v[12:13] op_sel_hi:[1,0,1]
	global_store_dwordx4 v125, v[12:15], s[2:3] offset:2048 nt
	v_mov_b64_e32 v[126:127], v[188:189]
	v_mov_b64_e32 v[128:129], v[190:191]
	v_pk_mul_f32 v[118:119], v[146:147], v[128:129]
	v_pk_mul_f32 v[126:127], v[140:141], v[126:127]
	v_pk_fma_f32 v[18:19], v[118:119], v[144:145], v[18:19] op_sel_hi:[1,0,1]
	v_pk_fma_f32 v[16:17], v[126:127], v[144:145], v[16:17] op_sel_hi:[1,0,1]
	global_store_dwordx4 v125, v[16:19], s[2:3] offset:3072 nt
	v_mov_b64_e32 v[126:127], v[192:193]
	v_mov_b64_e32 v[128:129], v[194:195]
	v_pk_mul_f32 v[118:119], v[150:151], v[128:129]
	v_pk_mul_f32 v[126:127], v[142:143], v[126:127]
	v_pk_fma_f32 v[22:23], v[118:119], v[144:145], v[22:23] op_sel_hi:[1,0,1]
	v_pk_fma_f32 v[20:21], v[126:127], v[144:145], v[20:21] op_sel_hi:[1,0,1]
	global_store_dwordx4 v124, v[20:23], s[2:3] nt
	v_mov_b64_e32 v[124:125], v[196:197]
	v_mov_b64_e32 v[126:127], v[198:199]
	v_mov_b32_e32 v118, v149
	v_mov_b32_e32 v119, v153
	v_mov_b32_e32 v149, v152
	v_pk_mul_f32 v[118:119], v[126:127], v[118:119]
	v_pk_mul_f32 v[124:125], v[124:125], v[148:149]
	v_pk_fma_f32 v[26:27], v[144:145], v[118:119], v[26:27] op_sel_hi:[0,1,1]
	v_pk_fma_f32 v[24:25], v[144:145], v[124:125], v[24:25] op_sel_hi:[0,1,1]
	global_store_dwordx4 v123, v[24:27], s[2:3] nt
	v_mov_b64_e32 v[124:125], v[200:201]
	v_mov_b64_e32 v[126:127], v[202:203]
	v_pk_mul_f32 v[118:119], v[164:165], v[126:127]
	v_pk_mul_f32 v[124:125], v[156:157], v[124:125]
	v_pk_fma_f32 v[30:31], v[144:145], v[118:119], v[30:31] op_sel_hi:[0,1,1]
	v_pk_fma_f32 v[28:29], v[144:145], v[124:125], v[28:29] op_sel_hi:[0,1,1]
	global_store_dwordx4 v122, v[28:31], s[2:3] nt
	v_mov_b64_e32 v[122:123], v[204:205]
	v_mov_b64_e32 v[124:125], v[206:207]
	v_pk_mul_f32 v[118:119], v[168:169], v[124:125]
	v_pk_mul_f32 v[122:123], v[160:161], v[122:123]
	v_pk_fma_f32 v[38:39], v[144:145], v[118:119], v[38:39] op_sel_hi:[0,1,1]
	v_pk_fma_f32 v[36:37], v[144:145], v[122:123], v[36:37] op_sel_hi:[0,1,1]
	global_store_dwordx4 v121, v[36:39], s[2:3] nt
	s_branch .LBB0_1899
